# P1 column-tile rotation 10 -> 6 (q,k,v tiles last)
# baseline (speedup 1.0000x reference)
.LBB0_103:
	s_cmp_lt_i32 s82, 2
	s_cselect_b64 s[4:5], -1, 0
	s_add_u32 s6, s80, 0x1100000
	v_writelane_b32 v255, s84, 25
	s_addc_u32 s7, s81, 0
	v_writelane_b32 v255, s6, 26
	s_nop 1
	v_writelane_b32 v255, s7, 27
	s_add_u32 s6, s80, 0x1300000
	s_addc_u32 s7, s81, 0
	v_writelane_b32 v255, s6, 28
	s_nop 1
	v_writelane_b32 v255, s7, 29
	s_add_u32 s6, s80, 0x1b00000
	s_addc_u32 s7, s81, 0
	s_add_u32 s69, s80, 0x2600000
	v_writelane_b32 v255, s6, 30
	s_addc_u32 s70, s81, 0
	s_nop 0
	v_writelane_b32 v255, s7, 31
	s_add_u32 s6, s80, 0x2c00000
	s_addc_u32 s7, s81, 0
	s_add_u32 s60, s80, 0x8c00000
	s_addc_u32 s61, s81, 0
	s_add_u32 s96, s80, 0xdc00000
	s_addc_u32 s91, s81, 0
	s_add_u32 s62, s80, 0x7c00000
	v_writelane_b32 v255, s6, 32
	s_addc_u32 s63, s81, 0
	s_and_b64 s[28:29], s[4:5], s[0:1]
	v_writelane_b32 v255, s7, 33
	s_andn2_b64 vcc, exec, s[28:29]
	s_cbranch_vccnz .LBB0_220
	s_cmpk_lt_i32 s2, 0x590
	s_cselect_b64 s[4:5], -1, 0
	s_cmpk_gt_i32 s2, 0x58f
	v_readfirstlane_b32 s6, v216
	s_cbranch_scc1 .LBB0_107
	s_cmpk_gt_i32 s2, 0x57f
	s_cbranch_scc1 .LBB0_108
	s_ashr_i32 s0, s2, 31
	s_lshr_b32 s0, s0, 29
	s_add_i32 s0, s2, s0
	s_ashr_i32 s1, s0, 3
	s_and_b32 s0, s0, -8
	s_sub_i32 s0, s2, s0
	s_cmp_lt_i32 s0, 0
	s_movk_i32 s7, 0xb1
	s_cselect_b32 s7, s7, 0xb0
	s_mul_i32 s0, s0, s7
	s_add_i32 s0, s0, s1
	s_mul_hi_i32 s1, s0, 0x2e8ba2e9
	s_lshr_b32 s7, s1, 31
	s_ashr_i32 s1, s1, 5
	s_add_i32 s1, s1, s7
	s_lshl_b32 s7, s1, 3
	s_mulk_i32 s1, 0xb0
	s_sub_i32 s0, s0, s1
	s_sext_i32_i16 s1, s0
	s_bfe_u32 s1, s1, 0x3001c
	s_add_i32 s1, s0, s1
	s_bfe_u32 s8, s1, 0xd0003
	s_and_b32 s1, s1, 0xfff8
	s_sub_i32 s0, s0, s1
	s_sext_i32_i16 s0, s0
	s_add_i32 s8, s8, 6
	s_add_i32 s38, s7, s0
	s_bfe_i32 s0, s8, 0x80000
	s_mul_i32 s0, s0, 0xffbb
	s_bfe_u32 s0, s0, 0x80008
	s_add_i32 s0, s0, s8
	s_bfe_i32 s1, s0, 0x80000
	s_and_b32 s1, 0xffff, s1
	s_lshr_b32 s1, s1, 4
	s_bfe_u32 s0, s0, 0x10007
	s_add_i32 s0, s1, s0
	s_mul_i32 s0, s0, 22
	s_sub_i32 s0, s8, s0
	s_mov_b32 s59, 0
	s_sext_i32_i8 s90, s0
	s_mov_b64 s[0:1], -1
	s_andn2_b64 vcc, exec, s[4:5]
	v_lshlrev_b32_e32 v16, 2, v216
	s_cbranch_vccz .LBB0_109
	s_branch .LBB0_178

.LBB0_117:
	s_andn2_b64 vcc, exec, s[12:13]
	s_mov_b32 s69, 1
	s_cbranch_vccnz .LBB0_119
	s_ashr_i32 s5, s4, 31
	s_lshr_b32 s5, s5, 29
	s_add_i32 s5, s4, s5
	s_ashr_i32 s12, s5, 3
	s_and_b32 s5, s5, -8
	s_sub_i32 s4, s4, s5
	s_cmp_lt_i32 s4, 0
	s_movk_i32 s5, 0xb1
	s_cselect_b32 s5, s5, 0xb0
	s_mul_i32 s4, s4, s5
	s_add_i32 s4, s4, s12
	s_mul_hi_i32 s5, s4, 0x2e8ba2e9
	s_lshr_b32 s12, s5, 31
	s_ashr_i32 s5, s5, 5
	s_add_i32 s5, s5, s12
	s_lshl_b32 s12, s5, 3
	s_sub_i32 s13, 64, s12
	s_min_i32 s13, s13, 8
	s_abs_i32 s14, s13
	v_cvt_f32_u32_e32 v0, s14
	s_sub_i32 s16, 0, s14
	s_mulk_i32 s5, 0xb0
	s_sub_i32 s4, s4, s5
	v_rcp_iflag_f32_e32 v0, v0
	s_abs_i32 s5, s4
	s_xor_b32 s15, s4, s13
	s_ashr_i32 s15, s15, 31
	v_mul_f32_e32 v0, 0x4f7ffffe, v0
	v_cvt_u32_f32_e32 v0, v0
	s_mov_b32 s69, 0
	v_readfirstlane_b32 s17, v0
	s_mul_i32 s16, s16, s17
	s_mul_hi_u32 s16, s17, s16
	s_add_i32 s17, s17, s16
	s_mul_hi_u32 s16, s5, s17
	s_mul_i32 s17, s16, s14
	s_sub_i32 s5, s5, s17
	s_add_i32 s17, s16, 1
	s_sub_i32 s18, s5, s14
	s_cmp_ge_u32 s5, s14
	s_cselect_b32 s16, s17, s16
	s_cselect_b32 s5, s18, s5
	s_add_i32 s17, s16, 1
	s_cmp_ge_u32 s5, s14
	s_cselect_b32 s5, s17, s16
	s_xor_b32 s5, s5, s15
	s_sub_i32 s5, s5, s15
	s_mul_i32 s13, s5, s13
	s_sub_i32 s4, s4, s13
	s_add_i32 s5, s5, 6
	s_add_i32 s42, s12, s4
	s_sext_i32_i16 s4, s5
	s_mulk_i32 s4, 0xba3
	s_lshr_b32 s12, s4, 31
	s_lshr_b32 s4, s4, 16
	s_add_i32 s4, s4, s12
	s_mul_i32 s4, s4, 22
	s_sub_i32 s4, s5, s4
	s_sext_i32_i16 s44, s4
